# GELU tile loop: first K-tile's 16 fragment reads hoisted to the tile-loop header ahead of the next-tile arithmetic (as in the other four loops)
# baseline (speedup 1.0000x reference)
; #define PG8_STAGE(bufoff, gbase, voff) do { _Pragma("unroll") for (int _i = 0; _i < 2; ++_i) { \
;         const unsigned _m0 = ldsb + (unsigned)((bufoff) + _i * 8192); const char* _gb = (const char*)(gbase); \
;         asm volatile("s_mov_b32 m0, %0\n\ts_nop 0\n\tglobal_load_lds_dwordx4 %1, %2" :: "s"(_m0), "v"((voff)[_i]), "s"(_gb) : "m0", "memory"); } } while (0)
; #define PG8_LDA(dst, b, h) do { _Pragma("unroll") for (int m = 0; m < 4; ++m) _Pragma("unroll") for (int k = 0; k < 2; ++k) dst[m][k] = *(const LAS bf16x8*)(lds + PG8_SA(b, h) + aoff + m * 2048 + k * 1024); } while (0)
; #define PG8_LDB(dst, b, h) do { _Pragma("unroll") for (int n = 0; n < 2; ++n) _Pragma("unroll") for (int k = 0; k < 2; ++k) dst[n][k] = *(const LAS bf16x8*)(lds + PG8_SB(b, h) + boff + n * 2048 + k * 1024); } while (0)
; #define PG8_SCHED __builtin_amdgcn_sched_barrier(0)
;     __device__ bool next(int i, Unit& u) const {
;         const long L = (long)i * G + c; if (L >= nwg) return false;
;         int wgid = (int)L; { const int q = nwg / NXCD, r = nwg % NXCD, xcd = wgid % NXCD, off = wgid / NXCD; wgid = (xcd < r ? xcd * (q + 1) : r * (q + 1) + (xcd - r) * q) + off; }
; template <class Epi, bool ALIGN_EPI>
; __device__ __forceinline__ void gemm_phase(LAS unsigned char* lds, const Gemm g, const StaticOrder& S, const Epi& E) {
;     ...
;         const bool has_next = S.next(ui + 1, nxt);
;         const char* nA = has_next ? (const char*)g.A + (size_t)nxt.pm * tstepA + (size_t)nxt.pn * g.a_pn_off * 2 + (size_t)(nxt.pm >> 4) * g.a_adj : cA; const char* nB = has_next ? (const char*)g.Bt + (size_t)nxt.pn * tstepB : cB;
;         for (int t = 0; t < nt; t += 2) {
;             const bool last = (t == nt - 2);
;             const char* a1 = cA + (size_t)(t + 1) * kstep;
;             const char* a2 = last ? nA : cA + (size_t)(t + 2) * kstep; const char* b2 = last ? nB : cB + (size_t)(t + 2) * kstep;
;             const char* a3 = a2 + kstep; const char* b3 = b2 + kstep;
;             PG8_LDB(B0, 0, 0); PG8_LDB(B1, 0, 1); PG8_SCHED; PG8_LDA(At, 0, 0); PG8_STAGE(PG8_SA(1, 1), a1 + hstepA, voffA);
.LBB0_342:
	v_add_u32_e32 v0, 0x10000, v187
	ds_read_b128 v[34:37], v0
	ds_read_b128 v[54:57], v0 offset:1024
	ds_read_b128 v[74:77], v0 offset:2048
	ds_read_b128 v[94:97], v0 offset:3072
	v_add_u32_e32 v0, 0x14000, v187
	ds_read_b128 v[110:113], v0
	ds_read_b128 v[126:129], v0 offset:1024
	ds_read_b128 v[146:149], v0 offset:2048
	ds_read_b128 v[160:163], v0 offset:3072
	ds_read_b128 v[164:167], v188
	ds_read_b128 v[168:171], v188 offset:1024
	ds_read_b128 v[172:175], v188 offset:2048
	ds_read_b128 v[176:179], v188 offset:3072
	ds_read_b128 v[190:193], v188 offset:4096
	ds_read_b128 v[202:205], v188 offset:5120
	ds_read_b128 v[206:209], v188 offset:6144
	ds_read_b128 v[210:213], v188 offset:7168
	s_add_i32 s92, s92, 1
	s_mul_i32 s4, s92, s94
	s_mul_hi_u32 s5, s92, s87
	s_add_i32 s5, s5, s4
	s_mul_i32 s4, s92, s87
	s_add_u32 s4, s4, s16
	s_addc_u32 s5, s5, s95
	v_mov_b64_e32 v[2:3], 0x400
	v_cmp_lt_i64_e64 s[8:9], s[4:5], v[2:3]
	v_mov_b64_e32 v[2:3], 0x3ff
	v_cmp_gt_i64_e32 vcc, s[4:5], v[2:3]
	s_cbranch_vccnz .LBB0_348
	s_ashr_i32 s5, s4, 31
	s_lshr_b32 s5, s5, 29
	s_add_i32 s11, s4, s5
	s_and_b32 s5, s11, -8
	s_sub_i32 s26, s4, s5
	s_cmp_gt_i32 s26, -1
	s_mov_b64 s[4:5], -1
	s_cbranch_scc0 .LBB0_345
	s_lshl_b32 s27, s26, 7
	s_mov_b64 s[4:5], 0

; #define PG8_STAGE(bufoff, gbase, voff) do { _Pragma("unroll") for (int _i = 0; _i < 2; ++_i) { \
;         const unsigned _m0 = ldsb + (unsigned)((bufoff) + _i * 8192); const char* _gb = (const char*)(gbase); \
;         asm volatile("s_mov_b32 m0, %0\n\ts_nop 0\n\tglobal_load_lds_dwordx4 %1, %2" :: "s"(_m0), "v"((voff)[_i]), "s"(_gb) : "m0", "memory"); } } while (0)
; #define PG8_LDA(dst, b, h) do { _Pragma("unroll") for (int m = 0; m < 4; ++m) _Pragma("unroll") for (int k = 0; k < 2; ++k) dst[m][k] = *(const LAS bf16x8*)(lds + PG8_SA(b, h) + aoff + m * 2048 + k * 1024); } while (0)
; #define PG8_LDB(dst, b, h) do { _Pragma("unroll") for (int n = 0; n < 2; ++n) _Pragma("unroll") for (int k = 0; k < 2; ++k) dst[n][k] = *(const LAS bf16x8*)(lds + PG8_SB(b, h) + boff + n * 2048 + k * 1024); } while (0)
; #define PG8_WAIT_V(n) asm volatile("s_waitcnt vmcnt(" #n ")" ::: "memory")
; #define PG8_WAIT_L(n) asm volatile("s_waitcnt lgkmcnt(" #n ")" ::: "memory")
; #define PG8_BAR __builtin_amdgcn_s_barrier()
; #define PG8_SCHED __builtin_amdgcn_sched_barrier(0)
; template <class Epi, bool ALIGN_EPI>
; __device__ __forceinline__ void gemm_phase(LAS unsigned char* lds, const Gemm g, const StaticOrder& S, const Epi& E) {
;     ...
;         const char* nA = has_next ? (const char*)g.A + (size_t)nxt.pm * tstepA + (size_t)nxt.pn * g.a_pn_off * 2 + (size_t)(nxt.pm >> 4) * g.a_adj : cA; const char* nB = has_next ? (const char*)g.Bt + (size_t)nxt.pn * tstepB : cB;
;         for (int t = 0; t < nt; t += 2) {
;             const bool last = (t == nt - 2);
;             const char* a1 = cA + (size_t)(t + 1) * kstep;
;             const char* a2 = last ? nA : cA + (size_t)(t + 2) * kstep; const char* b2 = last ? nB : cB + (size_t)(t + 2) * kstep;
;             const char* a3 = a2 + kstep; const char* b3 = b2 + kstep;
;             PG8_LDB(B0, 0, 0); PG8_LDB(B1, 0, 1); PG8_SCHED; PG8_LDA(At, 0, 0); PG8_STAGE(PG8_SA(1, 1), a1 + hstepA, voffA);
;             PG8_WAIT_V(8); PG8_WAIT_L(0); PG8_BAR; PG8_MMA(0, 0, At, B0); PG8_MMA(0, 1, At, B1); PG8_BAR; PG8_SCHED;
;             PG8_LDA(At, 0, 1); PG8_STAGE(PG8_SB(0, 0), b2, voffB); PG8_STAGE(PG8_SB(0, 1), b2 + hstepB, voffB); PG8_STAGE(PG8_SA(0, 0), a2, voffA);
;             PG8_WAIT_V(8); PG8_WAIT_L(0); PG8_BAR; PG8_MMA(1, 0, At, B0); PG8_MMA(1, 1, At, B1); PG8_BAR; PG8_SCHED;
.LBB0_348:
	s_ashr_i32 s29, s28, 31
	s_lshl_b64 s[4:5], s[28:29], 19
	s_add_u32 s30, s18, s4
	s_addc_u32 s31, s19, s5
	s_and_b64 s[4:5], s[8:9], exec
	s_cselect_b32 s4, s31, s39
	s_cselect_b32 s5, s30, s38
	s_ashr_i32 s27, s26, 31
	s_lshl_b64 s[34:35], s[26:27], 19
	s_add_u32 s34, s14, s34
	s_addc_u32 s35, s15, s35
	s_and_b64 s[48:49], s[8:9], exec
	s_cselect_b32 s11, s35, s37
	s_cselect_b32 s27, s34, s36
	s_add_u32 s29, s36, 0x100
	s_addc_u32 s41, s37, 0
	s_add_u32 s36, s38, 0x40080
	s_addc_u32 s37, s39, 0
	s_mov_b32 s50, -2
	s_add_u32 s38, s36, 0xfffc0080
	s_addc_u32 s39, s37, -1
	s_cmp_eq_u32 s50, 12
	s_cselect_b32 s54, s5, s38
	s_cselect_b32 s55, s4, s39
	s_cselect_b32 s48, s27, s29
	s_cselect_b32 s49, s11, s41
	s_add_u32 s38, s54, 0x80
	s_addc_u32 s39, s55, 0
	s_mov_b32 m0, s91
	s_nop 0
	global_load_lds_dwordx4 v180, s[36:37]
	s_nop 0
	s_mov_b32 m0, s93
	s_nop 0
	global_load_lds_dwordx4 v182, s[36:37]
	s_waitcnt vmcnt(8)
	s_waitcnt lgkmcnt(0)
	s_setprio 1
	s_barrier
	v_mfma_f32_16x16x32_bf16 v[154:157], v[34:37], v[164:167], 0
	v_mfma_f32_16x16x32_bf16 v[154:157], v[54:57], v[168:171], v[154:157]
	v_mfma_f32_16x16x32_bf16 v[150:153], v[74:77], v[164:167], 0
	v_mfma_f32_16x16x32_bf16 v[150:153], v[94:97], v[168:171], v[150:153]
	v_mfma_f32_16x16x32_bf16 v[142:145], v[110:113], v[164:167], 0
	v_mfma_f32_16x16x32_bf16 v[142:145], v[126:129], v[168:171], v[142:145]
	v_mfma_f32_16x16x32_bf16 v[138:141], v[146:149], v[164:167], 0
	v_mfma_f32_16x16x32_bf16 v[138:141], v[160:163], v[168:171], v[138:141]
	v_mfma_f32_16x16x32_bf16 v[118:121], v[146:149], v[172:175], 0
	v_mfma_f32_16x16x32_bf16 v[118:121], v[160:163], v[176:179], v[118:121]
	v_mfma_f32_16x16x32_bf16 v[122:125], v[110:113], v[172:175], 0
	v_mfma_f32_16x16x32_bf16 v[122:125], v[126:129], v[176:179], v[122:125]
	v_mfma_f32_16x16x32_bf16 v[130:133], v[74:77], v[172:175], 0
	v_mfma_f32_16x16x32_bf16 v[130:133], v[94:97], v[176:179], v[130:133]
	v_mfma_f32_16x16x32_bf16 v[134:137], v[34:37], v[172:175], 0
	v_mfma_f32_16x16x32_bf16 v[134:137], v[54:57], v[176:179], v[134:137]
	v_mfma_f32_16x16x32_bf16 v[114:117], v[34:37], v[190:193], 0
	v_mfma_f32_16x16x32_bf16 v[114:117], v[54:57], v[202:205], v[114:117]
	v_mfma_f32_16x16x32_bf16 v[106:109], v[74:77], v[190:193], 0
	v_mfma_f32_16x16x32_bf16 v[106:109], v[94:97], v[202:205], v[106:109]
	v_mfma_f32_16x16x32_bf16 v[102:105], v[110:113], v[190:193], 0
	v_mfma_f32_16x16x32_bf16 v[102:105], v[126:129], v[202:205], v[102:105]
	v_mfma_f32_16x16x32_bf16 v[98:101], v[146:149], v[190:193], 0
	v_mfma_f32_16x16x32_bf16 v[98:101], v[160:163], v[202:205], v[98:101]
	v_mfma_f32_16x16x32_bf16 v[78:81], v[146:149], v[206:209], 0
	v_mfma_f32_16x16x32_bf16 v[78:81], v[160:163], v[210:213], v[78:81]
	v_mfma_f32_16x16x32_bf16 v[82:85], v[110:113], v[206:209], 0
	v_mfma_f32_16x16x32_bf16 v[82:85], v[126:129], v[210:213], v[82:85]
	v_mfma_f32_16x16x32_bf16 v[86:89], v[74:77], v[206:209], 0
	v_mfma_f32_16x16x32_bf16 v[86:89], v[94:97], v[210:213], v[86:89]
	v_mfma_f32_16x16x32_bf16 v[90:93], v[34:37], v[206:209], 0
	v_mfma_f32_16x16x32_bf16 v[90:93], v[54:57], v[210:213], v[90:93]
	s_barrier
	s_setprio 0
	ds_read_b128 v[164:167], v188 offset:16384
	ds_read_b128 v[168:171], v188 offset:17408
	ds_read_b128 v[172:175], v188 offset:18432
	ds_read_b128 v[176:179], v188 offset:19456
	ds_read_b128 v[190:193], v188 offset:20480
	ds_read_b128 v[202:205], v188 offset:21504
	ds_read_b128 v[206:209], v188 offset:22528
	ds_read_b128 v[210:213], v188 offset:23552
	s_mov_b32 m0, s43
	s_nop 0
	global_load_lds_dwordx4 v181, s[48:49]
	s_add_u32 s96, s48, 0x40000
	s_mov_b32 m0, s44
	s_nop 0
	global_load_lds_dwordx4 v183, s[48:49]
	s_addc_u32 s97, s49, 0
	s_mov_b32 m0, s45
	s_nop 0
	global_load_lds_dwordx4 v181, s[96:97]
	s_nop 0
	s_mov_b32 m0, s56
	s_nop 0
	global_load_lds_dwordx4 v183, s[96:97]
	s_nop 0
	s_mov_b32 m0, s42
	s_nop 0
	global_load_lds_dwordx4 v180, s[54:55]
	s_nop 0
	s_mov_b32 m0, s57
	s_nop 0
	global_load_lds_dwordx4 v182, s[54:55]
	s_waitcnt vmcnt(8)
	s_waitcnt lgkmcnt(0)
	s_setprio 1
	s_barrier
	v_mfma_f32_16x16x32_bf16 v[70:73], v[34:37], v[164:167], 0
	v_mfma_f32_16x16x32_bf16 v[66:69], v[74:77], v[164:167], 0
	v_mfma_f32_16x16x32_bf16 v[50:53], v[34:37], v[172:175], 0
	v_mfma_f32_16x16x32_bf16 v[46:49], v[74:77], v[172:175], 0
	v_mfma_f32_16x16x32_bf16 v[30:33], v[34:37], v[190:193], 0
	v_mfma_f32_16x16x32_bf16 v[26:29], v[74:77], v[190:193], 0
	v_mfma_f32_16x16x32_bf16 v[14:17], v[34:37], v[206:209], 0
	v_mfma_f32_16x16x32_bf16 v[10:13], v[74:77], v[206:209], 0
	v_mfma_f32_16x16x32_bf16 v[70:73], v[54:57], v[168:171], v[70:73]
	v_mfma_f32_16x16x32_bf16 v[66:69], v[94:97], v[168:171], v[66:69]
	v_mfma_f32_16x16x32_bf16 v[50:53], v[54:57], v[176:179], v[50:53]
	v_mfma_f32_16x16x32_bf16 v[46:49], v[94:97], v[176:179], v[46:49]
	v_mfma_f32_16x16x32_bf16 v[30:33], v[54:57], v[202:205], v[30:33]
	v_mfma_f32_16x16x32_bf16 v[26:29], v[94:97], v[202:205], v[26:29]
	v_mfma_f32_16x16x32_bf16 v[14:17], v[54:57], v[210:213], v[14:17]
	v_mfma_f32_16x16x32_bf16 v[10:13], v[94:97], v[210:213], v[10:13]
	s_setprio 0
	s_setprio 1
	v_mfma_f32_16x16x32_bf16 v[42:45], v[110:113], v[172:175], 0
	v_mfma_f32_16x16x32_bf16 v[38:41], v[146:149], v[172:175], 0
	v_mfma_f32_16x16x32_bf16 v[22:25], v[110:113], v[190:193], 0
	v_mfma_f32_16x16x32_bf16 v[18:21], v[146:149], v[190:193], 0
	v_mfma_f32_16x16x32_bf16 v[6:9], v[110:113], v[206:209], 0
	v_mfma_f32_16x16x32_bf16 v[2:5], v[146:149], v[206:209], 0
	v_mfma_f32_16x16x32_bf16 v[34:37], v[110:113], v[164:167], 0
	v_mfma_f32_16x16x32_bf16 v[54:57], v[146:149], v[164:167], 0
	v_mfma_f32_16x16x32_bf16 v[42:45], v[126:129], v[176:179], v[42:45]
	v_mfma_f32_16x16x32_bf16 v[38:41], v[160:163], v[176:179], v[38:41]
	v_mfma_f32_16x16x32_bf16 v[22:25], v[126:129], v[202:205], v[22:25]
	v_mfma_f32_16x16x32_bf16 v[18:21], v[160:163], v[202:205], v[18:21]
	v_mfma_f32_16x16x32_bf16 v[6:9], v[126:129], v[210:213], v[6:9]
	v_mfma_f32_16x16x32_bf16 v[2:5], v[160:163], v[210:213], v[2:5]
	v_mfma_f32_16x16x32_bf16 v[34:37], v[126:129], v[168:171], v[34:37]
	v_mfma_f32_16x16x32_bf16 v[54:57], v[160:163], v[168:171], v[54:57]
	s_barrier
; #define PG8_STAGE(bufoff, gbase, voff) do { _Pragma("unroll") for (int _i = 0; _i < 2; ++_i) { \
;         const unsigned _m0 = ldsb + (unsigned)((bufoff) + _i * 8192); const char* _gb = (const char*)(gbase); \
;         asm volatile("s_mov_b32 m0, %0\n\ts_nop 0\n\tglobal_load_lds_dwordx4 %1, %2" :: "s"(_m0), "v"((voff)[_i]), "s"(_gb) : "m0", "memory"); } } while (0)
; #define PG8_LDA(dst, b, h) do { _Pragma("unroll") for (int m = 0; m < 4; ++m) _Pragma("unroll") for (int k = 0; k < 2; ++k) dst[m][k] = *(const LAS bf16x8*)(lds + PG8_SA(b, h) + aoff + m * 2048 + k * 1024); } while (0)
; #define PG8_LDB(dst, b, h) do { _Pragma("unroll") for (int n = 0; n < 2; ++n) _Pragma("unroll") for (int k = 0; k < 2; ++k) dst[n][k] = *(const LAS bf16x8*)(lds + PG8_SB(b, h) + boff + n * 2048 + k * 1024); } while (0)
; #define PG8_MMA(ai, bj, At, Bt) do { __builtin_amdgcn_s_setprio(1); _Pragma("unroll") for (int m = 0; m < 4; ++m) _Pragma("unroll") for (int n = 0; n < 2; ++n) _Pragma("unroll") for (int k = 0; k < 2; ++k) \
;         acc[ai][bj][m][n] = __builtin_amdgcn_mfma_f32_16x16x32_bf16(Bt[n][k], At[m][k], acc[ai][bj][m][n], 0, 0, 0); __builtin_amdgcn_s_setprio(0); } while (0)
; #define PG8_WAIT_V(n) asm volatile("s_waitcnt vmcnt(" #n ")" ::: "memory")
; #define PG8_WAIT_L(n) asm volatile("s_waitcnt lgkmcnt(" #n ")" ::: "memory")
; #define PG8_BAR __builtin_amdgcn_s_barrier()
; #define PG8_SCHED __builtin_amdgcn_sched_barrier(0)
; template <class Epi, bool ALIGN_EPI>
; __device__ __forceinline__ void gemm_phase(LAS unsigned char* lds, const Gemm g, const StaticOrder& S, const Epi& E) {
;     ...
;             PG8_LDB(B0, 1, 0); PG8_LDB(B1, 1, 1); PG8_SCHED; PG8_LDA(At, 1, 0); PG8_STAGE(PG8_SA(0, 1), a2 + hstepA, voffA);
;             PG8_WAIT_V(8); PG8_WAIT_L(0); PG8_BAR; PG8_MMA(0, 0, At, B0); PG8_MMA(0, 1, At, B1); PG8_BAR; PG8_SCHED;
;             PG8_LDA(At, 1, 1); PG8_STAGE(PG8_SB(1, 0), b3, voffB); PG8_STAGE(PG8_SB(1, 1), b3 + hstepB, voffB); PG8_STAGE(PG8_SA(1, 0), a3, voffA);
;             PG8_WAIT_V(8); PG8_WAIT_L(0); PG8_BAR; PG8_MMA(1, 0, At, B0); PG8_MMA(1, 1, At, B1); PG8_BAR; PG8_SCHED;
;         }
	s_setprio 0
	v_add_u32_e32 v0, 0x18000, v187
	ds_read_b128 v[58:61], v0
	ds_read_b128 v[62:65], v0 offset:1024
	ds_read_b128 v[74:77], v0 offset:2048
	ds_read_b128 v[94:97], v0 offset:3072
	v_add_u32_e32 v0, 0x1c000, v187
	ds_read_b128 v[110:113], v0
	ds_read_b128 v[126:129], v0 offset:1024
	ds_read_b128 v[146:149], v0 offset:2048
	ds_read_b128 v[160:163], v0 offset:3072
	ds_read_b128 v[164:167], v188 offset:32768
	ds_read_b128 v[168:171], v188 offset:33792
	ds_read_b128 v[172:175], v188 offset:34816
	ds_read_b128 v[176:179], v188 offset:35840
	ds_read_b128 v[190:193], v188 offset:36864
	ds_read_b128 v[202:205], v188 offset:37888
	ds_read_b128 v[206:209], v188 offset:38912
	ds_read_b128 v[210:213], v188 offset:39936
	s_add_u32 s54, s54, 0x40000
	s_addc_u32 s55, s55, 0
	s_mov_b32 m0, s58
	s_nop 0
	global_load_lds_dwordx4 v180, s[54:55]
	s_nop 0
	s_mov_b32 m0, s59
	s_nop 0
	global_load_lds_dwordx4 v182, s[54:55]
	s_waitcnt vmcnt(8)
	s_waitcnt lgkmcnt(0)
	s_setprio 1
	s_barrier
	v_mfma_f32_16x16x32_bf16 v[154:157], v[58:61], v[164:167], v[154:157]
	v_mfma_f32_16x16x32_bf16 v[154:157], v[62:65], v[168:171], v[154:157]
	v_mfma_f32_16x16x32_bf16 v[150:153], v[74:77], v[164:167], v[150:153]
	v_mfma_f32_16x16x32_bf16 v[150:153], v[94:97], v[168:171], v[150:153]
	v_mfma_f32_16x16x32_bf16 v[142:145], v[110:113], v[164:167], v[142:145]
	v_mfma_f32_16x16x32_bf16 v[142:145], v[126:129], v[168:171], v[142:145]
	v_mfma_f32_16x16x32_bf16 v[138:141], v[146:149], v[164:167], v[138:141]
	v_mfma_f32_16x16x32_bf16 v[138:141], v[160:163], v[168:171], v[138:141]
	v_mfma_f32_16x16x32_bf16 v[118:121], v[146:149], v[172:175], v[118:121]
	v_mfma_f32_16x16x32_bf16 v[118:121], v[160:163], v[176:179], v[118:121]
	v_mfma_f32_16x16x32_bf16 v[122:125], v[110:113], v[172:175], v[122:125]
	v_mfma_f32_16x16x32_bf16 v[122:125], v[126:129], v[176:179], v[122:125]
	v_mfma_f32_16x16x32_bf16 v[130:133], v[74:77], v[172:175], v[130:133]
	v_mfma_f32_16x16x32_bf16 v[130:133], v[94:97], v[176:179], v[130:133]
	v_mfma_f32_16x16x32_bf16 v[134:137], v[58:61], v[172:175], v[134:137]
	v_mfma_f32_16x16x32_bf16 v[134:137], v[62:65], v[176:179], v[134:137]
	v_mfma_f32_16x16x32_bf16 v[114:117], v[58:61], v[190:193], v[114:117]
	v_mfma_f32_16x16x32_bf16 v[114:117], v[62:65], v[202:205], v[114:117]
	v_mfma_f32_16x16x32_bf16 v[106:109], v[74:77], v[190:193], v[106:109]
	v_mfma_f32_16x16x32_bf16 v[106:109], v[94:97], v[202:205], v[106:109]
	v_mfma_f32_16x16x32_bf16 v[102:105], v[110:113], v[190:193], v[102:105]
	v_mfma_f32_16x16x32_bf16 v[102:105], v[126:129], v[202:205], v[102:105]
	v_mfma_f32_16x16x32_bf16 v[98:101], v[146:149], v[190:193], v[98:101]
	v_mfma_f32_16x16x32_bf16 v[98:101], v[160:163], v[202:205], v[98:101]
	v_mfma_f32_16x16x32_bf16 v[78:81], v[146:149], v[206:209], v[78:81]
	v_mfma_f32_16x16x32_bf16 v[78:81], v[160:163], v[210:213], v[78:81]
	v_mfma_f32_16x16x32_bf16 v[82:85], v[110:113], v[206:209], v[82:85]
	v_mfma_f32_16x16x32_bf16 v[82:85], v[126:129], v[210:213], v[82:85]
	v_mfma_f32_16x16x32_bf16 v[86:89], v[74:77], v[206:209], v[86:89]
	v_mfma_f32_16x16x32_bf16 v[86:89], v[94:97], v[210:213], v[86:89]
	v_mfma_f32_16x16x32_bf16 v[90:93], v[58:61], v[206:209], v[90:93]
	v_mfma_f32_16x16x32_bf16 v[90:93], v[62:65], v[210:213], v[90:93]
	s_barrier
	s_setprio 0
	ds_read_b128 v[164:167], v188 offset:49152
	ds_read_b128 v[168:171], v188 offset:50176
	ds_read_b128 v[172:175], v188 offset:51200
	ds_read_b128 v[176:179], v188 offset:52224
	ds_read_b128 v[190:193], v188 offset:53248
	ds_read_b128 v[202:205], v188 offset:54272
	ds_read_b128 v[206:209], v188 offset:55296
	ds_read_b128 v[210:213], v188 offset:56320
	s_add_u32 s54, s48, 0x80
	s_addc_u32 s55, s49, 0
	s_mov_b32 m0, s17
	s_nop 0
	global_load_lds_dwordx4 v181, s[54:55]
	s_add_u32 s48, s48, 0x40080
	s_mov_b32 m0, s60
	s_nop 0
	global_load_lds_dwordx4 v183, s[54:55]
	s_addc_u32 s49, s49, 0
	s_mov_b32 m0, s89
	s_nop 0
	global_load_lds_dwordx4 v181, s[48:49]
	s_nop 0
	s_mov_b32 m0, s90
	s_nop 0
	global_load_lds_dwordx4 v183, s[48:49]
	s_nop 0
	s_mov_b32 m0, s61
	s_nop 0
	global_load_lds_dwordx4 v180, s[38:39]
	s_nop 0
	s_mov_b32 m0, s88
	s_nop 0
	global_load_lds_dwordx4 v182, s[38:39]
	s_waitcnt vmcnt(8)
	s_waitcnt lgkmcnt(0)
	s_setprio 1
	s_barrier
	v_mfma_f32_16x16x32_bf16 v[70:73], v[58:61], v[164:167], v[70:73]
	v_mfma_f32_16x16x32_bf16 v[66:69], v[74:77], v[164:167], v[66:69]
	v_mfma_f32_16x16x32_bf16 v[50:53], v[58:61], v[172:175], v[50:53]
	v_mfma_f32_16x16x32_bf16 v[46:49], v[74:77], v[172:175], v[46:49]
	v_mfma_f32_16x16x32_bf16 v[30:33], v[58:61], v[190:193], v[30:33]
	v_mfma_f32_16x16x32_bf16 v[26:29], v[74:77], v[190:193], v[26:29]
	v_mfma_f32_16x16x32_bf16 v[14:17], v[58:61], v[206:209], v[14:17]
	v_mfma_f32_16x16x32_bf16 v[10:13], v[74:77], v[206:209], v[10:13]
	v_mfma_f32_16x16x32_bf16 v[70:73], v[62:65], v[168:171], v[70:73]
	v_mfma_f32_16x16x32_bf16 v[66:69], v[94:97], v[168:171], v[66:69]
	v_mfma_f32_16x16x32_bf16 v[50:53], v[62:65], v[176:179], v[50:53]
	v_mfma_f32_16x16x32_bf16 v[46:49], v[94:97], v[176:179], v[46:49]
	v_mfma_f32_16x16x32_bf16 v[30:33], v[62:65], v[202:205], v[30:33]
	v_mfma_f32_16x16x32_bf16 v[26:29], v[94:97], v[202:205], v[26:29]
	v_mfma_f32_16x16x32_bf16 v[14:17], v[62:65], v[210:213], v[14:17]
	v_mfma_f32_16x16x32_bf16 v[10:13], v[94:97], v[210:213], v[10:13]
	s_setprio 0
	s_setprio 1
	v_mfma_f32_16x16x32_bf16 v[34:37], v[110:113], v[164:167], v[34:37]
	v_mfma_f32_16x16x32_bf16 v[62:65], v[126:129], v[168:171], v[34:37]
	v_mfma_f32_16x16x32_bf16 v[34:37], v[146:149], v[164:167], v[54:57]
	v_mfma_f32_16x16x32_bf16 v[58:61], v[160:163], v[168:171], v[34:37]
	v_mfma_f32_16x16x32_bf16 v[34:37], v[110:113], v[172:175], v[42:45]
	v_mfma_f32_16x16x32_bf16 v[42:45], v[126:129], v[176:179], v[34:37]
	v_mfma_f32_16x16x32_bf16 v[34:37], v[146:149], v[172:175], v[38:41]
	v_mfma_f32_16x16x32_bf16 v[22:25], v[110:113], v[190:193], v[22:25]
	v_mfma_f32_16x16x32_bf16 v[18:21], v[146:149], v[190:193], v[18:21]
	v_mfma_f32_16x16x32_bf16 v[6:9], v[110:113], v[206:209], v[6:9]
	v_mfma_f32_16x16x32_bf16 v[2:5], v[146:149], v[206:209], v[2:5]
	v_mfma_f32_16x16x32_bf16 v[38:41], v[160:163], v[176:179], v[34:37]
	v_mfma_f32_16x16x32_bf16 v[22:25], v[126:129], v[202:205], v[22:25]
	v_mfma_f32_16x16x32_bf16 v[18:21], v[160:163], v[202:205], v[18:21]
	v_mfma_f32_16x16x32_bf16 v[6:9], v[126:129], v[210:213], v[6:9]
	v_mfma_f32_16x16x32_bf16 v[2:5], v[160:163], v[210:213], v[2:5]
	s_barrier
	s_setprio 0
	s_add_i32 s50, s50, 2
	s_add_u32 s29, s29, 0x100
	s_addc_u32 s41, s41, 0
	s_add_u32 s36, s36, 0x100
	s_addc_u32 s37, s37, 0
	s_cmp_gt_u32 s50, 13
